# P0 x->bf16 row sums: six-hop ds_bpermute butterfly replaced by DPP reduction + readlane broadcast
# baseline (speedup 1.0000x reference)
.LBB0_150:
	s_waitcnt vmcnt(3)
	v_mul_f32_e32 v78, v61, v61
	v_mul_f32_e32 v79, v63, v63
	v_fmac_f32_e32 v78, v60, v60
	v_fmac_f32_e32 v79, v62, v62
	v_add_f32_e32 v78, v78, v79
	s_waitcnt vmcnt(2)
	v_mul_f32_e32 v79, v57, v57
	v_mul_f32_e32 v80, v59, v59
	v_fmac_f32_e32 v79, v56, v56
	v_fmac_f32_e32 v80, v58, v58
	v_add_f32_e32 v79, v79, v80
	v_add_f32_e32 v78, v79, v78
	s_waitcnt vmcnt(1)
	v_mul_f32_e32 v79, v53, v53
	v_mul_f32_e32 v80, v55, v55
	v_fmac_f32_e32 v79, v52, v52
	v_fmac_f32_e32 v80, v54, v54
	v_add_f32_e32 v79, v79, v80
	v_add_f32_e32 v78, v79, v78
	s_waitcnt vmcnt(0)
	v_mul_f32_e32 v79, v49, v49
	v_mul_f32_e32 v80, v51, v51
	v_fmac_f32_e32 v79, v48, v48
	v_fmac_f32_e32 v80, v50, v50
	v_add_f32_e32 v79, v79, v80
	v_add_f32_e32 v78, v79, v78
	s_ashr_i32 s23, s22, 31
	s_nop 1
	v_add_f32_dpp v78, v78, v78 quad_perm:[1,0,3,2] row_mask:0xf bank_mask:0xf
	s_nop 1
	v_add_f32_dpp v78, v78, v78 quad_perm:[2,3,0,1] row_mask:0xf bank_mask:0xf
	s_nop 1
	v_add_f32_dpp v78, v78, v78 row_shr:4 row_mask:0xf bank_mask:0xf bound_ctrl:1
	s_nop 1
	v_add_f32_dpp v78, v78, v78 row_shr:8 row_mask:0xf bank_mask:0xf bound_ctrl:1
	s_nop 1
	v_add_f32_dpp v78, v78, v78 row_bcast:15 row_mask:0xa bank_mask:0xf
	s_nop 1
	v_add_f32_dpp v78, v78, v78 row_bcast:31 row_mask:0xc bank_mask:0xf
	s_nop 1
	v_readlane_b32 vcc_lo, v78, 63
	s_nop 1
	v_mov_b32_e32 v78, vcc_lo
	s_and_saveexec_b64 s[28:29], s[0:1]
	s_cbranch_execz .LBB0_154
	s_andn2_b64 vcc, exec, s[6:7]
	v_mov_b32_e32 v80, 0
	s_cbranch_vccnz .LBB0_153
	s_waitcnt lgkmcnt(0)
	v_fmamk_f32 v78, v78, 0x3a800000, v64
	v_mul_f32_e32 v79, 0x4f800000, v78
	v_cmp_gt_f32_e32 vcc, s31, v78
	s_nop 1
	v_cndmask_b32_e32 v78, v78, v79, vcc
	v_sqrt_f32_e32 v79, v78
	s_nop 0
	v_add_u32_e32 v80, -1, v79
	v_fma_f32 v82, -v80, v79, v78
	v_add_u32_e32 v81, 1, v79
	v_cmp_ge_f32_e64 s[6:7], 0, v82
	s_nop 1
	v_cndmask_b32_e64 v80, v79, v80, s[6:7]
	v_fma_f32 v79, -v81, v79, v78
	v_cmp_lt_f32_e64 s[6:7], 0, v79
	s_nop 1
	v_cndmask_b32_e64 v79, v80, v81, s[6:7]
	v_mul_f32_e32 v80, 0x37800000, v79
	v_cndmask_b32_e32 v79, v79, v80, vcc
	v_cmp_class_f32_e32 vcc, v78, v76
	s_nop 1
	v_cndmask_b32_e32 v78, v79, v78, vcc
	v_div_scale_f32 v79, s[6:7], v78, v78, 1.0
	v_rcp_f32_e32 v80, v79
	s_nop 0
	v_fma_f32 v81, -v79, v80, 1.0
	v_fmac_f32_e32 v80, v81, v80
	v_div_scale_f32 v81, vcc, 1.0, v78, 1.0
	v_mul_f32_e32 v82, v81, v80
	v_fma_f32 v83, -v79, v82, v81
	v_fmac_f32_e32 v82, v83, v80
	v_fma_f32 v79, -v79, v82, v81
	v_div_fmas_f32 v79, v79, v80, v82
	v_div_fixup_f32 v80, v79, v78, 1.0

.LBB0_157:
	v_mul_f32_e32 v32, v29, v29
	v_mul_f32_e32 v33, v31, v31
	v_fmac_f32_e32 v32, v28, v28
	v_fmac_f32_e32 v33, v30, v30
	v_add_f32_e32 v32, v32, v33
	v_mul_f32_e32 v33, v25, v25
	v_mul_f32_e32 v34, v27, v27
	v_fmac_f32_e32 v33, v24, v24
	v_fmac_f32_e32 v34, v26, v26
	v_add_f32_e32 v33, v33, v34
	v_add_f32_e32 v32, v33, v32
	v_mul_f32_e32 v33, v21, v21
	v_mul_f32_e32 v34, v23, v23
	v_fmac_f32_e32 v33, v20, v20
	v_fmac_f32_e32 v34, v22, v22
	v_add_f32_e32 v33, v33, v34
	v_add_f32_e32 v32, v33, v32
	v_mul_f32_e32 v33, v1, v1
	v_mul_f32_e32 v34, v3, v3
	v_fmac_f32_e32 v33, v0, v0
	v_fmac_f32_e32 v34, v2, v2
	v_add_f32_e32 v33, v33, v34
	v_add_f32_e32 v32, v33, v32
	s_ashr_i32 s17, s16, 31
	s_nop 1
	v_add_f32_dpp v32, v32, v32 quad_perm:[1,0,3,2] row_mask:0xf bank_mask:0xf
	s_nop 1
	v_add_f32_dpp v32, v32, v32 quad_perm:[2,3,0,1] row_mask:0xf bank_mask:0xf
	s_nop 1
	v_add_f32_dpp v32, v32, v32 row_shr:4 row_mask:0xf bank_mask:0xf bound_ctrl:1
	s_nop 1
	v_add_f32_dpp v32, v32, v32 row_shr:8 row_mask:0xf bank_mask:0xf bound_ctrl:1
	s_nop 1
	v_add_f32_dpp v32, v32, v32 row_bcast:15 row_mask:0xa bank_mask:0xf
	s_nop 1
	v_add_f32_dpp v32, v32, v32 row_bcast:31 row_mask:0xc bank_mask:0xf
	s_nop 1
	v_readlane_b32 vcc_lo, v32, 63
	s_nop 1
	v_mov_b32_e32 v32, vcc_lo
	s_and_saveexec_b64 s[22:23], s[0:1]
	s_cbranch_execz .LBB0_161
	s_andn2_b64 vcc, exec, s[20:21]
	v_mov_b32_e32 v34, 0
	s_cbranch_vccnz .LBB0_160
	s_waitcnt lgkmcnt(0)
	v_fmamk_f32 v32, v32, 0x3a800000, v64
	v_mul_f32_e32 v33, 0x4f800000, v32
	v_cmp_gt_f32_e32 vcc, s31, v32
	s_nop 1
	v_cndmask_b32_e32 v32, v32, v33, vcc
	v_sqrt_f32_e32 v33, v32
	s_nop 0
	v_add_u32_e32 v34, -1, v33
	v_fma_f32 v36, -v34, v33, v32
	v_add_u32_e32 v35, 1, v33
	v_cmp_ge_f32_e64 s[6:7], 0, v36
	s_nop 1
	v_cndmask_b32_e64 v34, v33, v34, s[6:7]
	v_fma_f32 v33, -v35, v33, v32
	v_cmp_lt_f32_e64 s[6:7], 0, v33
	s_nop 1
	v_cndmask_b32_e64 v33, v34, v35, s[6:7]
	v_mul_f32_e32 v34, 0x37800000, v33
	v_cndmask_b32_e32 v33, v33, v34, vcc
	v_cmp_class_f32_e32 vcc, v32, v76
	s_nop 1
	v_cndmask_b32_e32 v32, v33, v32, vcc
	v_div_scale_f32 v33, s[6:7], v32, v32, 1.0
	v_rcp_f32_e32 v34, v33
	s_nop 0
	v_fma_f32 v35, -v33, v34, 1.0
	v_fmac_f32_e32 v34, v35, v34
	v_div_scale_f32 v35, vcc, 1.0, v32, 1.0
	v_mul_f32_e32 v36, v35, v34
	v_fma_f32 v37, -v33, v36, v35
	v_fmac_f32_e32 v36, v37, v34
	v_fma_f32 v33, -v33, v36, v35
	v_div_fmas_f32 v33, v33, v34, v36
	v_div_fixup_f32 v34, v33, v32, 1.0

.LBB0_165:
	v_mul_f32_e32 v48, v45, v45
	v_mul_f32_e32 v49, v47, v47
	v_fmac_f32_e32 v48, v44, v44
	v_fmac_f32_e32 v49, v46, v46
	v_add_f32_e32 v48, v48, v49
	v_mul_f32_e32 v49, v41, v41
	v_mul_f32_e32 v50, v43, v43
	v_fmac_f32_e32 v49, v40, v40
	v_fmac_f32_e32 v50, v42, v42
	v_add_f32_e32 v49, v49, v50
	v_add_f32_e32 v48, v49, v48
	v_mul_f32_e32 v49, v37, v37
	v_mul_f32_e32 v50, v39, v39
	v_fmac_f32_e32 v49, v36, v36
	v_fmac_f32_e32 v50, v38, v38
	v_add_f32_e32 v49, v49, v50
	v_add_f32_e32 v48, v49, v48
	v_mul_f32_e32 v49, v33, v33
	v_mul_f32_e32 v50, v35, v35
	v_fmac_f32_e32 v49, v32, v32
	v_fmac_f32_e32 v50, v34, v34
	v_add_f32_e32 v49, v49, v50
	v_add_f32_e32 v48, v49, v48
	s_ashr_i32 s3, s2, 31
	s_nop 1
	v_add_f32_dpp v48, v48, v48 quad_perm:[1,0,3,2] row_mask:0xf bank_mask:0xf
	s_nop 1
	v_add_f32_dpp v48, v48, v48 quad_perm:[2,3,0,1] row_mask:0xf bank_mask:0xf
	s_nop 1
	v_add_f32_dpp v48, v48, v48 row_shr:4 row_mask:0xf bank_mask:0xf bound_ctrl:1
	s_nop 1
	v_add_f32_dpp v48, v48, v48 row_shr:8 row_mask:0xf bank_mask:0xf bound_ctrl:1
	s_nop 1
	v_add_f32_dpp v48, v48, v48 row_bcast:15 row_mask:0xa bank_mask:0xf
	s_nop 1
	v_add_f32_dpp v48, v48, v48 row_bcast:31 row_mask:0xc bank_mask:0xf
	s_nop 1
	v_readlane_b32 vcc_lo, v48, 63
	s_nop 1
	v_mov_b32_e32 v48, vcc_lo
	s_and_saveexec_b64 s[22:23], s[0:1]
	s_cbranch_execz .LBB0_169
	s_andn2_b64 vcc, exec, s[26:27]
	v_mov_b32_e32 v50, 0
	s_cbranch_vccnz .LBB0_168
	s_waitcnt lgkmcnt(0)
	v_fmamk_f32 v48, v48, 0x3a800000, v64
	v_mul_f32_e32 v49, 0x4f800000, v48
	v_cmp_gt_f32_e32 vcc, s31, v48
	s_nop 1
	v_cndmask_b32_e32 v48, v48, v49, vcc
	v_sqrt_f32_e32 v49, v48
	s_nop 0
	v_add_u32_e32 v50, -1, v49
	v_fma_f32 v52, -v50, v49, v48
	v_add_u32_e32 v51, 1, v49
	v_cmp_ge_f32_e64 s[6:7], 0, v52
	s_nop 1
	v_cndmask_b32_e64 v50, v49, v50, s[6:7]
	v_fma_f32 v49, -v51, v49, v48
	v_cmp_lt_f32_e64 s[6:7], 0, v49
	s_nop 1
	v_cndmask_b32_e64 v49, v50, v51, s[6:7]
	v_mul_f32_e32 v50, 0x37800000, v49
	v_cndmask_b32_e32 v49, v49, v50, vcc
	v_cmp_class_f32_e32 vcc, v48, v76
	s_nop 1
	v_cndmask_b32_e32 v48, v49, v48, vcc
	v_div_scale_f32 v49, s[6:7], v48, v48, 1.0
	v_rcp_f32_e32 v50, v49
	s_nop 0
	v_fma_f32 v51, -v49, v50, 1.0
	v_fmac_f32_e32 v50, v51, v50
	v_div_scale_f32 v51, vcc, 1.0, v48, 1.0
	v_mul_f32_e32 v52, v51, v50
	v_fma_f32 v53, -v49, v52, v51
	v_fmac_f32_e32 v52, v53, v50
	v_fma_f32 v49, -v49, v52, v51
	v_div_fmas_f32 v49, v49, v50, v52
	v_div_fixup_f32 v50, v49, v48, 1.0

.LBB0_173:
	v_mul_f32_e32 v0, v17, v17
	v_mul_f32_e32 v1, v19, v19
	v_fmac_f32_e32 v0, v16, v16
	v_fmac_f32_e32 v1, v18, v18
	v_add_f32_e32 v0, v0, v1
	v_mul_f32_e32 v1, v13, v13
	v_mul_f32_e32 v2, v15, v15
	v_fmac_f32_e32 v1, v12, v12
	v_fmac_f32_e32 v2, v14, v14
	v_add_f32_e32 v1, v1, v2
	v_add_f32_e32 v0, v1, v0
	v_mul_f32_e32 v1, v9, v9
	v_mul_f32_e32 v2, v11, v11
	v_fmac_f32_e32 v1, v8, v8
	v_fmac_f32_e32 v2, v10, v10
	v_add_f32_e32 v1, v1, v2
	v_add_f32_e32 v0, v1, v0
	v_mul_f32_e32 v1, v5, v5
	v_mul_f32_e32 v2, v7, v7
	v_fmac_f32_e32 v1, v4, v4
	v_fmac_f32_e32 v2, v6, v6
	v_add_f32_e32 v1, v1, v2
	v_add_f32_e32 v0, v1, v0
	s_ashr_i32 s15, s14, 31
	s_nop 1
	v_add_f32_dpp v0, v0, v0 quad_perm:[1,0,3,2] row_mask:0xf bank_mask:0xf
	s_nop 1
	v_add_f32_dpp v0, v0, v0 quad_perm:[2,3,0,1] row_mask:0xf bank_mask:0xf
	s_nop 1
	v_add_f32_dpp v0, v0, v0 row_shr:4 row_mask:0xf bank_mask:0xf bound_ctrl:1
	s_nop 1
	v_add_f32_dpp v0, v0, v0 row_shr:8 row_mask:0xf bank_mask:0xf bound_ctrl:1
	s_nop 1
	v_add_f32_dpp v0, v0, v0 row_bcast:15 row_mask:0xa bank_mask:0xf
	s_nop 1
	v_add_f32_dpp v0, v0, v0 row_bcast:31 row_mask:0xc bank_mask:0xf
	s_nop 1
	v_readlane_b32 vcc_lo, v0, 63
	s_nop 1
	v_mov_b32_e32 v0, vcc_lo
	s_and_saveexec_b64 s[16:17], s[0:1]
	s_cbranch_execz .LBB0_177
	s_andn2_b64 vcc, exec, s[18:19]
	v_mov_b32_e32 v2, 0
	s_cbranch_vccnz .LBB0_176
	s_waitcnt lgkmcnt(0)
	v_fmamk_f32 v0, v0, 0x3a800000, v64
	v_mul_f32_e32 v1, 0x4f800000, v0
	v_cmp_gt_f32_e32 vcc, s31, v0
	s_nop 1
	v_cndmask_b32_e32 v0, v0, v1, vcc
	v_sqrt_f32_e32 v1, v0
	s_nop 0
	v_add_u32_e32 v2, -1, v1
	v_fma_f32 v20, -v2, v1, v0
	v_add_u32_e32 v3, 1, v1
	v_cmp_ge_f32_e64 s[6:7], 0, v20
	s_nop 1
	v_cndmask_b32_e64 v2, v1, v2, s[6:7]
	v_fma_f32 v1, -v3, v1, v0
	v_cmp_lt_f32_e64 s[6:7], 0, v1
	s_nop 1
	v_cndmask_b32_e64 v1, v2, v3, s[6:7]
	v_mul_f32_e32 v2, 0x37800000, v1
	v_cndmask_b32_e32 v1, v1, v2, vcc
	v_cmp_class_f32_e32 vcc, v0, v76
	s_nop 1
	v_cndmask_b32_e32 v0, v1, v0, vcc
	v_div_scale_f32 v1, s[6:7], v0, v0, 1.0
	v_rcp_f32_e32 v2, v1
	s_nop 0
	v_fma_f32 v3, -v1, v2, 1.0
	v_fmac_f32_e32 v2, v3, v2
	v_div_scale_f32 v3, vcc, 1.0, v0, 1.0
	v_mul_f32_e32 v20, v3, v2
	v_fma_f32 v21, -v1, v20, v3
	v_fmac_f32_e32 v20, v21, v2
	v_fma_f32 v1, -v1, v20, v3
	v_div_fmas_f32 v1, v1, v2, v20
	v_div_fixup_f32 v2, v1, v0, 1.0
